# attention epilogue: the eight sub-LN gain vectors loaded once instead of 16 serialized load-wait-store rounds
# baseline (speedup 1.0000x reference)
.LBB0_721:
	s_or_b64 exec, exec, s[2:3]
	s_movk_i32 s2, 0x100
	v_cmp_gt_u32_e32 vcc, s2, v191
	s_and_b64 s[40:41], vcc, s[40:41]
	s_waitcnt lgkmcnt(0)
	s_barrier
	s_and_saveexec_b64 s[2:3], s[40:41]
	s_cbranch_execz .LBB0_723
	v_lshl_or_b32 v33, v33, 5, v193
	v_lshlrev_b32_e32 v99, 8, v191
	v_lshl_add_u32 v98, v38, 2, 0
	v_add_u32_e32 v38, s48, v33
	v_and_b32_e32 v33, 0xc000, v99
	v_add_u32_e32 v100, v98, v33
	s_waitcnt vmcnt(4)
	ds_read2st64_b32 v[50:51], v100 offset0:8 offset1:9
	s_waitcnt vmcnt(3)
	ds_read2st64_b32 v[52:53], v100 offset0:10 offset1:11
	ds_read2st64_b32 v[54:55], v100 offset0:12 offset1:13
	s_waitcnt vmcnt(2)
	ds_read2st64_b32 v[56:57], v100 offset0:14 offset1:15
	s_waitcnt vmcnt(0)
	v_sub_f32_e32 v97, 1.0, v35
	ds_read2st64_b32 v[34:35], v100 offset1:1
	ds_read2st64_b32 v[40:41], v100 offset0:2 offset1:3
	ds_read2st64_b32 v[46:47], v100 offset0:4 offset1:5
	ds_read2st64_b32 v[48:49], v100 offset0:6 offset1:7
	s_waitcnt lgkmcnt(5)
	v_pk_fma_f32 v[54:55], v[68:69], v[32:33], v[54:55] op_sel_hi:[1,0,1] neg_lo:[0,0,1] neg_hi:[0,0,1]
	s_waitcnt lgkmcnt(4)
	v_pk_fma_f32 v[68:69], v[70:71], v[32:33], v[56:57] op_sel_hi:[1,0,1] neg_lo:[0,0,1] neg_hi:[0,0,1]
	ds_read2st64_b32 v[56:57], v100 offset0:16 offset1:17
	ds_read2st64_b32 v[58:59], v100 offset0:30 offset1:31
	s_waitcnt lgkmcnt(5)
	v_pk_fma_f32 v[42:43], v[92:93], v[32:33], v[34:35] op_sel_hi:[1,0,1] neg_lo:[0,0,1] neg_hi:[0,0,1]
	s_waitcnt lgkmcnt(4)
	v_pk_fma_f32 v[44:45], v[94:95], v[32:33], v[40:41] op_sel_hi:[1,0,1] neg_lo:[0,0,1] neg_hi:[0,0,1]
	v_pk_mul_f32 v[34:35], v[42:43], v[42:43]
	s_waitcnt lgkmcnt(1)
	v_pk_fma_f32 v[70:71], v[64:65], v[32:33], v[56:57] op_sel_hi:[1,0,1] neg_lo:[0,0,1] neg_hi:[0,0,1]
	ds_read2st64_b32 v[56:57], v100 offset0:18 offset1:19
	v_pk_mul_f32 v[40:41], v[44:45], v[44:45]
	v_pk_fma_f32 v[50:51], v[80:81], v[32:33], v[50:51] op_sel_hi:[1,0,1] neg_lo:[0,0,1] neg_hi:[0,0,1]
	v_add_f32_e32 v34, v34, v35
	v_pk_fma_f32 v[46:47], v[88:89], v[32:33], v[46:47] op_sel_hi:[1,0,1] neg_lo:[0,0,1] neg_hi:[0,0,1]
	s_waitcnt lgkmcnt(0)
	v_pk_fma_f32 v[80:81], v[66:67], v[32:33], v[56:57] op_sel_hi:[1,0,1] neg_lo:[0,0,1] neg_hi:[0,0,1]
	ds_read2st64_b32 v[56:57], v100 offset0:20 offset1:21
	v_add_f32_e32 v34, v34, v40
	v_pk_mul_f32 v[88:89], v[46:47], v[46:47]
	v_add_f32_e32 v34, v34, v41
	v_pk_fma_f32 v[48:49], v[90:91], v[32:33], v[48:49] op_sel_hi:[1,0,1] neg_lo:[0,0,1] neg_hi:[0,0,1]
	v_add_f32_e32 v34, v34, v88
	v_pk_mul_f32 v[90:91], v[48:49], v[48:49]
	v_add_f32_e32 v34, v34, v89
	s_waitcnt lgkmcnt(0)
	v_pk_fma_f32 v[64:65], v[72:73], v[32:33], v[56:57] op_sel_hi:[1,0,1] neg_lo:[0,0,1] neg_hi:[0,0,1]
	ds_read2st64_b32 v[56:57], v100 offset0:22 offset1:23
	v_add_f32_e32 v34, v34, v90
	v_pk_mul_f32 v[92:93], v[50:51], v[50:51]
	v_add_f32_e32 v34, v34, v91
	v_pk_fma_f32 v[52:53], v[82:83], v[32:33], v[52:53] op_sel_hi:[1,0,1] neg_lo:[0,0,1] neg_hi:[0,0,1]
	v_add_f32_e32 v34, v34, v92
	v_pk_mul_f32 v[82:83], v[52:53], v[52:53]
	v_add_f32_e32 v34, v34, v93
	v_add_f32_e32 v34, v34, v82
	v_pk_mul_f32 v[94:95], v[54:55], v[54:55]
	s_waitcnt lgkmcnt(0)
	v_pk_fma_f32 v[66:67], v[74:75], v[32:33], v[56:57] op_sel_hi:[1,0,1] neg_lo:[0,0,1] neg_hi:[0,0,1]
	ds_read2st64_b32 v[56:57], v100 offset0:24 offset1:25
	v_add_f32_e32 v34, v34, v83
	v_add_f32_e32 v34, v34, v94
	v_pk_mul_f32 v[102:103], v[68:69], v[68:69]
	v_add_f32_e32 v34, v34, v95
	v_add_f32_e32 v34, v34, v102
	v_pk_mul_f32 v[104:105], v[70:71], v[70:71]
	v_add_f32_e32 v34, v34, v103
	s_waitcnt lgkmcnt(0)
	v_pk_fma_f32 v[60:61], v[76:77], v[32:33], v[56:57] op_sel_hi:[1,0,1] neg_lo:[0,0,1] neg_hi:[0,0,1]
	ds_read2st64_b32 v[56:57], v100 offset0:26 offset1:27
	v_add_f32_e32 v34, v34, v104
	v_pk_mul_f32 v[106:107], v[80:81], v[80:81]
	v_add_f32_e32 v34, v34, v105
	v_add_f32_e32 v34, v34, v106
	v_pk_mul_f32 v[72:73], v[64:65], v[64:65]
	v_add_f32_e32 v34, v34, v107
	v_add_f32_e32 v34, v34, v72
	v_pk_mul_f32 v[74:75], v[66:67], v[66:67]
	s_waitcnt lgkmcnt(0)
	v_pk_fma_f32 v[62:63], v[78:79], v[32:33], v[56:57] op_sel_hi:[1,0,1] neg_lo:[0,0,1] neg_hi:[0,0,1]
	ds_read2st64_b32 v[56:57], v100 offset0:28 offset1:29
	v_add_f32_e32 v34, v34, v73
	v_add_f32_e32 v34, v34, v74
	v_pk_mul_f32 v[76:77], v[60:61], v[60:61]
	v_add_f32_e32 v34, v34, v75
	v_add_f32_e32 v34, v34, v76
	v_pk_mul_f32 v[78:79], v[62:63], v[62:63]
	v_add_f32_e32 v34, v34, v77
	s_waitcnt lgkmcnt(0)
	v_pk_fma_f32 v[56:57], v[84:85], v[32:33], v[56:57] op_sel_hi:[1,0,1] neg_lo:[0,0,1] neg_hi:[0,0,1]
	v_add_f32_e32 v34, v34, v78
	v_pk_mul_f32 v[84:85], v[56:57], v[56:57]
	v_add_f32_e32 v34, v34, v79
	v_pk_fma_f32 v[58:59], v[86:87], v[32:33], v[58:59] op_sel_hi:[1,0,1] neg_lo:[0,0,1] neg_hi:[0,0,1]
	v_add_f32_e32 v34, v34, v84
	v_pk_mul_f32 v[32:33], v[58:59], v[58:59]
	v_add_f32_e32 v34, v34, v85
	v_add_f32_e32 v32, v34, v32
	v_add_f32_e32 v32, v32, v33
	ds_bpermute_b32 v33, v37, v32
	v_ashrrev_i32_e32 v39, 31, v38
	v_readlane_b32 s40, v249, 22
	v_ashrrev_i32_e32 v193, 31, v192
	v_readlane_b32 s41, v249, 23
	s_waitcnt lgkmcnt(0)
	v_add_f32_e32 v32, v32, v33
	ds_bpermute_b32 v33, v96, v32
	v_lshlrev_b64 v[40:41], 1, v[192:193]
	v_readlane_b32 s42, v249, 26
	v_mov_b32_e32 v191, v177
	v_readlane_b32 s43, v249, 27
	s_waitcnt lgkmcnt(0)
	v_add_f32_e32 v32, v32, v33
	v_fmamk_f32 v32, v32, 0x3c000000, v228
	v_rsq_f32_e32 v32, v32
	s_nop 0
	v_mul_f32_e32 v72, v97, v32
	v_lshlrev_b64 v[32:33], 11, v[38:39]
	v_lshl_add_u64 v[32:33], s[40:41], 0, v[32:33]
	v_lshl_add_u64 v[32:33], v[32:33], 0, v[40:41]
	v_lshl_add_u64 v[74:75], v[32:33], 0, v[190:191]
	global_load_dwordx4 v[112:115], v176, s[42:43]
	global_load_dwordx4 v[116:119], v176, s[42:43] offset:64
	global_load_dwordx4 v[120:123], v176, s[42:43] offset:128
	global_load_dwordx4 v[124:127], v176, s[42:43] offset:192
	global_load_dwordx4 v[128:131], v176, s[42:43] offset:256
	global_load_dwordx4 v[132:135], v176, s[42:43] offset:320
	global_load_dwordx4 v[136:139], v176, s[42:43] offset:384
	global_load_dwordx4 v[140:143], v176, s[42:43] offset:448
	s_waitcnt vmcnt(0)
	v_pk_mul_f32 v[42:43], v[42:43], v[72:73] op_sel_hi:[1, 0]
	v_pk_mul_f32 v[44:45], v[44:45], v[72:73] op_sel_hi:[1, 0]
	v_pk_mul_f32 v[32:33], v[112:113], v[42:43]
	v_pk_mul_f32 v[34:35], v[114:115], v[44:45]
	v_cvt_pk_bf16_f32 v32, v32, v33
	v_cvt_pk_bf16_f32 v33, v34, v35
	global_store_dwordx2 v[74:75], v[32:33], off offset:1024
	v_pk_mul_f32 v[42:43], v[46:47], v[72:73] op_sel_hi:[1, 0]
	v_pk_mul_f32 v[44:45], v[48:49], v[72:73] op_sel_hi:[1, 0]
	v_pk_mul_f32 v[32:33], v[116:117], v[42:43]
	v_pk_mul_f32 v[34:35], v[118:119], v[44:45]
	v_cvt_pk_bf16_f32 v32, v32, v33
	v_cvt_pk_bf16_f32 v33, v34, v35
	global_store_dwordx2 v[74:75], v[32:33], off offset:1056
	v_pk_mul_f32 v[42:43], v[50:51], v[72:73] op_sel_hi:[1, 0]
	v_pk_mul_f32 v[44:45], v[52:53], v[72:73] op_sel_hi:[1, 0]
	v_pk_mul_f32 v[32:33], v[120:121], v[42:43]
	v_pk_mul_f32 v[34:35], v[122:123], v[44:45]
	v_cvt_pk_bf16_f32 v32, v32, v33
	v_cvt_pk_bf16_f32 v33, v34, v35
	global_store_dwordx2 v[74:75], v[32:33], off offset:1088
	v_pk_mul_f32 v[42:43], v[54:55], v[72:73] op_sel_hi:[1, 0]
	v_pk_mul_f32 v[44:45], v[68:69], v[72:73] op_sel_hi:[1, 0]
	v_pk_mul_f32 v[32:33], v[124:125], v[42:43]
	v_pk_mul_f32 v[34:35], v[126:127], v[44:45]
	v_cvt_pk_bf16_f32 v32, v32, v33
	v_cvt_pk_bf16_f32 v33, v34, v35
	global_store_dwordx2 v[74:75], v[32:33], off offset:1120
	v_pk_mul_f32 v[42:43], v[70:71], v[72:73] op_sel_hi:[1, 0]
	v_pk_mul_f32 v[44:45], v[80:81], v[72:73] op_sel_hi:[1, 0]
	v_pk_mul_f32 v[32:33], v[128:129], v[42:43]
	v_pk_mul_f32 v[34:35], v[130:131], v[44:45]
	v_cvt_pk_bf16_f32 v32, v32, v33
	v_cvt_pk_bf16_f32 v33, v34, v35
	global_store_dwordx2 v[74:75], v[32:33], off offset:1152
	v_pk_mul_f32 v[42:43], v[64:65], v[72:73] op_sel_hi:[1, 0]
	v_pk_mul_f32 v[44:45], v[66:67], v[72:73] op_sel_hi:[1, 0]
	v_pk_mul_f32 v[32:33], v[42:43], v[132:133]
	v_pk_mul_f32 v[34:35], v[44:45], v[134:135]
	v_cvt_pk_bf16_f32 v32, v32, v33
	v_cvt_pk_bf16_f32 v33, v34, v35
	global_store_dwordx2 v[74:75], v[32:33], off offset:1184
	v_pk_mul_f32 v[42:43], v[60:61], v[72:73] op_sel_hi:[1, 0]
	v_pk_mul_f32 v[44:45], v[62:63], v[72:73] op_sel_hi:[1, 0]
	v_pk_mul_f32 v[32:33], v[42:43], v[136:137]
	v_pk_mul_f32 v[34:35], v[44:45], v[138:139]
	v_cvt_pk_bf16_f32 v32, v32, v33
	v_cvt_pk_bf16_f32 v33, v34, v35
	global_store_dwordx2 v[74:75], v[32:33], off offset:1216
	v_pk_mul_f32 v[42:43], v[56:57], v[72:73] op_sel_hi:[1, 0]
	v_pk_mul_f32 v[44:45], v[58:59], v[72:73] op_sel_hi:[1, 0]
	v_pk_mul_f32 v[32:33], v[42:43], v[140:141]
	v_pk_mul_f32 v[34:35], v[44:45], v[142:143]
	v_cvt_pk_bf16_f32 v32, v32, v33
	v_cvt_pk_bf16_f32 v33, v34, v35
	global_store_dwordx2 v[74:75], v[32:33], off offset:1248
	ds_read2st64_b32 v[32:33], v100 offset0:32 offset1:33
	s_waitcnt lgkmcnt(0)
	v_pk_fma_f32 v[48:49], v[4:5], v[36:37], v[32:33] op_sel_hi:[1,0,1] neg_lo:[0,0,1] neg_hi:[0,0,1]
	ds_read2st64_b32 v[4:5], v100 offset0:34 offset1:35
	v_pk_mul_f32 v[52:53], v[48:49], v[48:49]
	s_waitcnt lgkmcnt(0)
	v_pk_fma_f32 v[50:51], v[6:7], v[36:37], v[4:5] op_sel_hi:[1,0,1] neg_lo:[0,0,1] neg_hi:[0,0,1]
	ds_read2st64_b32 v[4:5], v100 offset0:36 offset1:37
	v_pk_mul_f32 v[54:55], v[50:51], v[50:51]
	s_waitcnt lgkmcnt(0)
	v_pk_fma_f32 v[44:45], v[8:9], v[36:37], v[4:5] op_sel_hi:[1,0,1] neg_lo:[0,0,1] neg_hi:[0,0,1]
	ds_read2st64_b32 v[4:5], v100 offset0:38 offset1:39
	v_pk_mul_f32 v[56:57], v[44:45], v[44:45]
	s_waitcnt lgkmcnt(0)
	v_pk_fma_f32 v[46:47], v[10:11], v[36:37], v[4:5] op_sel_hi:[1,0,1] neg_lo:[0,0,1] neg_hi:[0,0,1]
	ds_read2st64_b32 v[4:5], v100 offset0:40 offset1:41
	v_pk_mul_f32 v[58:59], v[46:47], v[46:47]
	s_waitcnt lgkmcnt(0)
	v_pk_fma_f32 v[34:35], v[12:13], v[36:37], v[4:5] op_sel_hi:[1,0,1] neg_lo:[0,0,1] neg_hi:[0,0,1]
	ds_read2st64_b32 v[4:5], v100 offset0:42 offset1:43
	v_pk_mul_f32 v[60:61], v[34:35], v[34:35]
	s_waitcnt lgkmcnt(0)
	v_pk_fma_f32 v[42:43], v[14:15], v[36:37], v[4:5] op_sel_hi:[1,0,1] neg_lo:[0,0,1] neg_hi:[0,0,1]
	ds_read2st64_b32 v[4:5], v100 offset0:44 offset1:45
	v_pk_mul_f32 v[62:63], v[42:43], v[42:43]
	s_waitcnt lgkmcnt(0)
	v_pk_fma_f32 v[32:33], v[16:17], v[36:37], v[4:5] op_sel_hi:[1,0,1] neg_lo:[0,0,1] neg_hi:[0,0,1]
	ds_read2st64_b32 v[4:5], v100 offset0:46 offset1:47
	v_pk_mul_f32 v[64:65], v[32:33], v[32:33]
	s_waitcnt lgkmcnt(0)
	v_pk_fma_f32 v[18:19], v[18:19], v[36:37], v[4:5] op_sel_hi:[1,0,1] neg_lo:[0,0,1] neg_hi:[0,0,1]
	ds_read2st64_b32 v[4:5], v100 offset0:48 offset1:49
	v_pk_mul_f32 v[66:67], v[18:19], v[18:19]
	s_waitcnt lgkmcnt(0)
	v_pk_fma_f32 v[14:15], v[20:21], v[36:37], v[4:5] op_sel_hi:[1,0,1] neg_lo:[0,0,1] neg_hi:[0,0,1]
	ds_read2st64_b32 v[4:5], v100 offset0:50 offset1:51
	ds_read_b32 v20, v100 offset:15872
	v_or_b32_e32 v21, 0x3f00, v99
	v_add_u32_e32 v21, v98, v21
	ds_read_b32 v21, v21
	s_waitcnt lgkmcnt(2)
	v_pk_fma_f32 v[16:17], v[22:23], v[36:37], v[4:5] op_sel_hi:[1,0,1] neg_lo:[0,0,1] neg_hi:[0,0,1]
	ds_read2st64_b32 v[4:5], v100 offset0:52 offset1:53
	v_pk_mul_f32 v[68:69], v[14:15], v[14:15]
	v_pk_mul_f32 v[22:23], v[16:17], v[16:17]
	s_waitcnt lgkmcnt(1)
	v_pk_fma_f32 v[20:21], v[2:3], v[36:37], v[20:21] op_sel_hi:[1,0,1] neg_lo:[0,0,1] neg_hi:[0,0,1]
	s_waitcnt lgkmcnt(0)
	v_pk_fma_f32 v[10:11], v[24:25], v[36:37], v[4:5] op_sel_hi:[1,0,1] neg_lo:[0,0,1] neg_hi:[0,0,1]
	ds_read2st64_b32 v[4:5], v100 offset0:54 offset1:55
	v_pk_mul_f32 v[24:25], v[10:11], v[10:11]
	v_pk_mul_f32 v[2:3], v[20:21], v[20:21]
	s_waitcnt lgkmcnt(0)
	v_pk_fma_f32 v[12:13], v[26:27], v[36:37], v[4:5] op_sel_hi:[1,0,1] neg_lo:[0,0,1] neg_hi:[0,0,1]
	ds_read2st64_b32 v[4:5], v100 offset0:56 offset1:57
	v_pk_mul_f32 v[26:27], v[12:13], v[12:13]
	s_waitcnt lgkmcnt(0)
	v_pk_fma_f32 v[6:7], v[28:29], v[36:37], v[4:5] op_sel_hi:[1,0,1] neg_lo:[0,0,1] neg_hi:[0,0,1]
	ds_read2st64_b32 v[4:5], v100 offset0:58 offset1:59
	v_pk_mul_f32 v[28:29], v[6:7], v[6:7]
	s_waitcnt lgkmcnt(0)
	v_pk_fma_f32 v[8:9], v[30:31], v[36:37], v[4:5] op_sel_hi:[1,0,1] neg_lo:[0,0,1] neg_hi:[0,0,1]
	ds_read2st64_b32 v[4:5], v100 offset0:60 offset1:61
	v_pk_mul_f32 v[30:31], v[8:9], v[8:9]
	s_waitcnt lgkmcnt(0)
	v_pk_fma_f32 v[4:5], v[0:1], v[36:37], v[4:5] op_sel_hi:[1,0,1] neg_lo:[0,0,1] neg_hi:[0,0,1]
	v_add_f32_e32 v36, v52, v53
	v_add_f32_e32 v36, v36, v54
	v_add_f32_e32 v36, v36, v55
	v_add_f32_e32 v36, v36, v56
	v_add_f32_e32 v36, v36, v57
	v_add_f32_e32 v36, v36, v58
	v_add_f32_e32 v36, v36, v59
	v_add_f32_e32 v36, v36, v60
	v_add_f32_e32 v36, v36, v61
	v_add_f32_e32 v36, v36, v62
	v_add_f32_e32 v36, v36, v63
	v_add_f32_e32 v36, v36, v64
	v_add_f32_e32 v36, v36, v65
	v_add_f32_e32 v36, v36, v66
	v_add_f32_e32 v36, v36, v67
	v_add_f32_e32 v36, v36, v68
	v_add_f32_e32 v36, v36, v69
	v_add_f32_e32 v22, v36, v22
	v_add_f32_e32 v22, v22, v23
	v_add_f32_e32 v22, v22, v24
	v_add_f32_e32 v22, v22, v25
	v_add_f32_e32 v22, v22, v26
	v_add_f32_e32 v22, v22, v27
	v_add_f32_e32 v22, v22, v28
	v_add_f32_e32 v22, v22, v29
	v_add_f32_e32 v22, v22, v30
	v_pk_mul_f32 v[0:1], v[4:5], v[4:5]
	v_add_f32_e32 v22, v22, v31
	v_add_f32_e32 v0, v22, v0
	v_add_f32_e32 v0, v0, v1
	v_add_f32_e32 v0, v0, v2
	v_add_f32_e32 v0, v0, v3
	ds_bpermute_b32 v1, v37, v0
	s_waitcnt lgkmcnt(0)
	v_add_f32_e32 v0, v0, v1
	ds_bpermute_b32 v1, v96, v0
	s_waitcnt lgkmcnt(0)
	v_add_f32_e32 v0, v0, v1
	v_fmamk_f32 v0, v0, 0x3c000000, v228
	v_rsq_f32_e32 v0, v0
	s_nop 0
	v_mul_f32_e32 v24, v97, v0
	v_add_u32_e32 v0, 16, v38
	v_ashrrev_i32_e32 v1, 31, v0
	v_lshlrev_b64 v[0:1], 11, v[0:1]
	v_lshl_add_u64 v[0:1], s[40:41], 0, v[0:1]
	v_lshl_add_u64 v[0:1], v[0:1], 0, v[40:41]
	v_lshl_add_u64 v[22:23], v[0:1], 0, v[190:191]
	v_pk_mul_f32 v[26:27], v[48:49], v[24:25] op_sel_hi:[1, 0]
	v_pk_mul_f32 v[28:29], v[50:51], v[24:25] op_sel_hi:[1, 0]
	v_pk_mul_f32 v[18:19], v[18:19], v[24:25] op_sel_hi:[1, 0]
	v_pk_mul_f32 v[14:15], v[14:15], v[24:25] op_sel_hi:[1, 0]
	v_pk_mul_f32 v[16:17], v[16:17], v[24:25] op_sel_hi:[1, 0]
	v_pk_mul_f32 v[10:11], v[10:11], v[24:25] op_sel_hi:[1, 0]
	v_pk_mul_f32 v[12:13], v[12:13], v[24:25] op_sel_hi:[1, 0]
	v_pk_mul_f32 v[6:7], v[6:7], v[24:25] op_sel_hi:[1, 0]
	v_pk_mul_f32 v[8:9], v[8:9], v[24:25] op_sel_hi:[1, 0]
	v_pk_mul_f32 v[4:5], v[4:5], v[24:25] op_sel_hi:[1, 0]
	v_pk_mul_f32 v[2:3], v[114:115], v[28:29]
	v_pk_mul_f32 v[0:1], v[112:113], v[26:27]
	v_pk_mul_f32 v[26:27], v[44:45], v[24:25] op_sel_hi:[1, 0]
	v_cvt_pk_bf16_f32 v0, v0, v1
	v_cvt_pk_bf16_f32 v1, v2, v3
	global_store_dwordx2 v[22:23], v[0:1], off offset:1024
	v_pk_mul_f32 v[28:29], v[46:47], v[24:25] op_sel_hi:[1, 0]
	v_pk_mul_f32 v[0:1], v[116:117], v[26:27]
	v_pk_mul_f32 v[2:3], v[118:119], v[28:29]
	v_cvt_pk_bf16_f32 v0, v0, v1
	v_cvt_pk_bf16_f32 v1, v2, v3
	global_store_dwordx2 v[22:23], v[0:1], off offset:1056
	v_pk_mul_f32 v[26:27], v[34:35], v[24:25] op_sel_hi:[1, 0]
	v_pk_mul_f32 v[28:29], v[42:43], v[24:25] op_sel_hi:[1, 0]
	v_pk_mul_f32 v[0:1], v[120:121], v[26:27]
	v_pk_mul_f32 v[2:3], v[122:123], v[28:29]
	v_cvt_pk_bf16_f32 v0, v0, v1
	v_cvt_pk_bf16_f32 v1, v2, v3
	global_store_dwordx2 v[22:23], v[0:1], off offset:1088
	v_pk_mul_f32 v[26:27], v[32:33], v[24:25] op_sel_hi:[1, 0]
	v_pk_mul_f32 v[2:3], v[126:127], v[18:19]
	v_pk_mul_f32 v[0:1], v[124:125], v[26:27]
	s_nop 0
	v_cvt_pk_bf16_f32 v0, v0, v1
	v_cvt_pk_bf16_f32 v1, v2, v3
	global_store_dwordx2 v[22:23], v[0:1], off offset:1120
	v_pk_mul_f32 v[2:3], v[130:131], v[16:17]
	v_pk_mul_f32 v[0:1], v[128:129], v[14:15]
	s_nop 0
	v_cvt_pk_bf16_f32 v0, v0, v1
	v_cvt_pk_bf16_f32 v1, v2, v3
	global_store_dwordx2 v[22:23], v[0:1], off offset:1152
	v_pk_mul_f32 v[2:3], v[12:13], v[134:135]
	v_pk_mul_f32 v[0:1], v[10:11], v[132:133]
	s_nop 0
	v_cvt_pk_bf16_f32 v0, v0, v1
	v_cvt_pk_bf16_f32 v1, v2, v3
	global_store_dwordx2 v[22:23], v[0:1], off offset:1184
	v_pk_mul_f32 v[2:3], v[8:9], v[138:139]
	v_pk_mul_f32 v[0:1], v[6:7], v[136:137]
	v_pk_mul_f32 v[6:7], v[20:21], v[24:25] op_sel_hi:[1, 0]
	v_cvt_pk_bf16_f32 v0, v0, v1
	v_cvt_pk_bf16_f32 v1, v2, v3
	global_store_dwordx2 v[22:23], v[0:1], off offset:1216
	v_pk_mul_f32 v[2:3], v[6:7], v[142:143]
	v_pk_mul_f32 v[0:1], v[4:5], v[140:141]
	s_nop 0
	v_cvt_pk_bf16_f32 v0, v0, v1
	v_cvt_pk_bf16_f32 v1, v2, v3
	global_store_dwordx2 v[22:23], v[0:1], off offset:1248
